# k8 plus the same up-front P-fragment reads with counted waits for row groups 1 and 3 of the mixer-B pv waves
# speedup vs baseline: 1.0124x; 1.0124x over previous
; __device__ __forceinline__ void attn_b2_unit(int b, int h, int qk, int jlo, const bf16_t* __restrict__ P, bf16_t* __restrict__ mix, const float* __restrict__ subg, float lam,
;                                              float* __restrict__ o0s, char* lds) {
;     ...
;                             const char* pp = lds + B2_P + (pb * 4 + rg) * 4096 + lane * 16;
;                             const bf16x8 pa0 = *(const bf16x8*)(pp), pa1 = *(const bf16x8*)(pp + 1024), pa2 = *(const bf16x8*)(pp + 2048), pa3 = *(const bf16x8*)(pp + 3072);
;                             o[2 * rg] = __builtin_amdgcn_mfma_f32_32x32x16_bf16(pa0, vf[0][0], o[2 * rg], 0, 0, 0); o[2 * rg + 1] = __builtin_amdgcn_mfma_f32_32x32x16_bf16(pa0, vf[1][0], o[2 * rg + 1], 0, 0, 0);
;                             o[2 * rg] = __builtin_amdgcn_mfma_f32_32x32x16_bf16(pa1, vf[0][1], o[2 * rg], 0, 0, 0); o[2 * rg + 1] = __builtin_amdgcn_mfma_f32_32x32x16_bf16(pa1, vf[1][1], o[2 * rg + 1], 0, 0, 0);
;                             o[2 * rg] = __builtin_amdgcn_mfma_f32_32x32x16_bf16(pa2, vf[0][2], o[2 * rg], 0, 0, 0); o[2 * rg + 1] = __builtin_amdgcn_mfma_f32_32x32x16_bf16(pa2, vf[1][2], o[2 * rg + 1], 0, 0, 0);
;                             o[2 * rg] = __builtin_amdgcn_mfma_f32_32x32x16_bf16(pa3, vf[0][3], o[2 * rg], 0, 0, 0); o[2 * rg + 1] = __builtin_amdgcn_mfma_f32_32x32x16_bf16(pa3, vf[1][3], o[2 * rg + 1], 0, 0, 0);
.LBB0_376:
	v_lshl_add_u32 v1, s2, 12, v168
	ds_read_b128 v[212:215], v1
	ds_read_b128 v[216:219], v1 offset:1024
	ds_read_b128 v[220:223], v1 offset:2048
	ds_read_b128 v[224:227], v1 offset:3072
	s_waitcnt lgkmcnt(3)
	v_mfma_f32_32x32x16_bf16 v[96:111], v[212:215], v[152:155], v[96:111]
	v_mfma_f32_32x32x16_bf16 v[80:95], v[212:215], v[160:163], v[80:95]
	s_waitcnt lgkmcnt(2)
	v_mfma_f32_32x32x16_bf16 v[96:111], v[216:219], v[148:151], v[96:111]
	v_mfma_f32_32x32x16_bf16 v[80:95], v[216:219], v[156:159], v[80:95]
	s_waitcnt lgkmcnt(1)
	v_mfma_f32_32x32x16_bf16 v[96:111], v[220:223], v[6:9], v[96:111]
	v_mfma_f32_32x32x16_bf16 v[80:95], v[220:223], v[144:147], v[80:95]
	s_waitcnt lgkmcnt(0)
	v_mfma_f32_32x32x16_bf16 v[96:111], v[224:227], v[2:5], v[96:111]
	v_mfma_f32_32x32x16_bf16 v[80:95], v[224:227], v[10:13], v[80:95]

; __device__ __forceinline__ void attn_b2_unit(int b, int h, int qk, int jlo, const bf16_t* __restrict__ P, bf16_t* __restrict__ mix, const float* __restrict__ subg, float lam,
;                                              float* __restrict__ o0s, char* lds) {
;     ...
;                             const char* pp = lds + B2_P + (pb * 4 + rg) * 4096 + lane * 16;
;                             const bf16x8 pa0 = *(const bf16x8*)(pp), pa1 = *(const bf16x8*)(pp + 1024), pa2 = *(const bf16x8*)(pp + 2048), pa3 = *(const bf16x8*)(pp + 3072);
;                             o[2 * rg] = __builtin_amdgcn_mfma_f32_32x32x16_bf16(pa0, vf[0][0], o[2 * rg], 0, 0, 0); o[2 * rg + 1] = __builtin_amdgcn_mfma_f32_32x32x16_bf16(pa0, vf[1][0], o[2 * rg + 1], 0, 0, 0);
;                             o[2 * rg] = __builtin_amdgcn_mfma_f32_32x32x16_bf16(pa1, vf[0][1], o[2 * rg], 0, 0, 0); o[2 * rg + 1] = __builtin_amdgcn_mfma_f32_32x32x16_bf16(pa1, vf[1][1], o[2 * rg + 1], 0, 0, 0);
;                             o[2 * rg] = __builtin_amdgcn_mfma_f32_32x32x16_bf16(pa2, vf[0][2], o[2 * rg], 0, 0, 0); o[2 * rg + 1] = __builtin_amdgcn_mfma_f32_32x32x16_bf16(pa2, vf[1][2], o[2 * rg + 1], 0, 0, 0);
;                             o[2 * rg] = __builtin_amdgcn_mfma_f32_32x32x16_bf16(pa3, vf[0][3], o[2 * rg], 0, 0, 0); o[2 * rg + 1] = __builtin_amdgcn_mfma_f32_32x32x16_bf16(pa3, vf[1][3], o[2 * rg + 1], 0, 0, 0);
.LBB0_381:
	v_lshl_add_u32 v1, s2, 12, v168
	ds_read_b128 v[212:215], v1
	ds_read_b128 v[216:219], v1 offset:1024
	ds_read_b128 v[220:223], v1 offset:2048
	ds_read_b128 v[224:227], v1 offset:3072
	s_waitcnt lgkmcnt(3)
	v_mfma_f32_32x32x16_bf16 v[32:47], v[212:215], v[152:155], v[32:47]
	v_mfma_f32_32x32x16_bf16 v[16:31], v[212:215], v[160:163], v[16:31]
	s_waitcnt lgkmcnt(2)
	v_mfma_f32_32x32x16_bf16 v[32:47], v[216:219], v[148:151], v[32:47]
	v_mfma_f32_32x32x16_bf16 v[16:31], v[216:219], v[156:159], v[16:31]
	s_waitcnt lgkmcnt(1)
	v_mfma_f32_32x32x16_bf16 v[32:47], v[220:223], v[6:9], v[32:47]
	v_mfma_f32_32x32x16_bf16 v[16:31], v[220:223], v[144:147], v[16:31]
	s_waitcnt lgkmcnt(0)
	v_mfma_f32_32x32x16_bf16 v[32:47], v[224:227], v[2:5], v[32:47]
	v_mfma_f32_32x32x16_bf16 v[16:31], v[224:227], v[10:13], v[16:31]
